# strategy 2: phase_mod silu staging (phase 0 and phase 3b) issues its 20 loads together with counted waits instead of one exposed round trip per element
# speedup vs baseline: 1.0077x; 1.0011x over previous
; __device__ __forceinline__ float siluf_(float x) { return x / (1.f + __expf(-x)); }
; __device__ __forceinline__ void phase_mod(const Params& p, unsigned char* lds, const int layer, const int wb0, const int nwb) {
;     const int tid = threadIdx.x;
;     float* sc = (float*)lds;
;     float* red = (float*)(lds + 40960);
;     float* modv = (float*)(p.ws + WS_MODV);
;     __syncthreads();
;     for (int e = tid; e < 5 * D; e += 512) { const int r = e / D, k = e % D; const float v = r < 4 ? p.c[r * D + k] : p.c_ctx[k]; sc[e] = siluf_(v); }
;     __syncthreads();
.LBB0_17:
	s_cmp_lt_i32 s80, 1
	s_cselect_b64 s[2:3], -1, 0
	s_cmp_gt_i32 s81, 0
	s_cselect_b64 s[4:5], -1, 0
	s_and_b64 s[2:3], s[2:3], s[4:5]
	s_andn2_b64 vcc, exec, s[2:3]
	v_lshlrev_b32_e32 v160, 2, v162
	s_cbranch_vccnz .LBB0_37
	v_mul_u32_u24_e32 v0, 0x1556, v162
	v_lshrrev_b32_e32 v32, 16, v0
	v_mul_lo_u16_e32 v0, 0xab, v162
	v_mov_b32_e32 v1, 0
	v_lshrrev_b16_e32 v7, 13, v0
	v_mov_b32_e32 v161, v1
	v_mul_u32_u24_e32 v6, 0x3000, v7
	v_mul_u32_u24_e32 v4, 0x3c0, v32
	v_mul_u32_u24_e32 v5, 0xc0, v7
	v_add_u32_e32 v8, 0, v160
	s_waitcnt lgkmcnt(0)
	v_lshl_add_u64 v[2:3], s[38:39], 0, v[160:161]
	s_mov_b64 s[4:5], 0
	s_movk_i32 s8, 0x2000
	s_mov_b64 s[6:7], 0x800
	s_movk_i32 s9, 0x25ff
	v_mov_b32_e32 v9, v162
	s_barrier
	v_mov_b32_e32 v220, v160
	global_load_dword v200, v220, s[38:39]
	global_load_dword v201, v220, s[38:39] offset:2048
	v_add_u32_e32 v220, 0x1000, v220
	global_load_dword v202, v220, s[38:39]
	global_load_dword v203, v220, s[38:39] offset:2048
	v_add_u32_e32 v220, 0x1000, v220
	global_load_dword v204, v220, s[38:39]
	global_load_dword v205, v220, s[38:39] offset:2048
	v_add_u32_e32 v220, 0x1000, v220
	global_load_dword v206, v220, s[38:39]
	global_load_dword v207, v220, s[38:39] offset:2048
	v_add_u32_e32 v220, 0x1000, v220
	global_load_dword v208, v220, s[38:39]
	global_load_dword v209, v220, s[38:39] offset:2048
	v_add_u32_e32 v220, 0x1000, v220
	global_load_dword v210, v220, s[38:39]
	global_load_dword v211, v220, s[38:39] offset:2048
	v_add_u32_e32 v220, 0x1000, v220
	global_load_dword v212, v220, s[38:39]
	global_load_dword v213, v220, s[38:39] offset:2048
	v_add_u32_e32 v220, 0x1000, v220
	global_load_dword v214, v220, s[38:39]
	global_load_dword v215, v220, s[38:39] offset:2048
	global_load_dword v216, v160, s[42:43]
	global_load_dword v217, v160, s[42:43] offset:2048
	v_add_u32_e32 v220, 0x1000, v160
	global_load_dword v218, v220, s[42:43]
	global_load_dword v219, v220, s[42:43] offset:2048
	s_waitcnt vmcnt(19)
	v_mul_f32_e32 v222, 0xbfb8aa3b, v200
	v_exp_f32_e32 v222, v222
	s_nop 0
	v_add_f32_e32 v222, 1.0, v222
	v_div_scale_f32 v223, s[10:11], v222, v222, v200
	v_rcp_f32_e32 v224, v223
	v_div_scale_f32 v225, vcc, v200, v222, v200
	v_fma_f32 v226, -v223, v224, 1.0
	v_fmac_f32_e32 v224, v226, v224
	v_mul_f32_e32 v226, v225, v224
	v_fma_f32 v227, -v223, v226, v225
	v_fmac_f32_e32 v226, v227, v224
	v_fma_f32 v223, -v223, v226, v225
	v_div_fmas_f32 v223, v223, v224, v226
	v_div_fixup_f32 v200, v223, v222, v200
	ds_write_b32 v160, v200
	s_waitcnt vmcnt(18)
	v_mul_f32_e32 v222, 0xbfb8aa3b, v201
	v_exp_f32_e32 v222, v222
	s_nop 0
	v_add_f32_e32 v222, 1.0, v222
	v_div_scale_f32 v223, s[10:11], v222, v222, v201
	v_rcp_f32_e32 v224, v223
	v_div_scale_f32 v225, vcc, v201, v222, v201
	v_fma_f32 v226, -v223, v224, 1.0
	v_fmac_f32_e32 v224, v226, v224
	v_mul_f32_e32 v226, v225, v224
	v_fma_f32 v227, -v223, v226, v225
	v_fmac_f32_e32 v226, v227, v224
	v_fma_f32 v223, -v223, v226, v225
	v_div_fmas_f32 v223, v223, v224, v226
	v_div_fixup_f32 v201, v223, v222, v201
	ds_write_b32 v160, v201 offset:2048
	s_waitcnt vmcnt(17)
	v_mul_f32_e32 v222, 0xbfb8aa3b, v202
	v_exp_f32_e32 v222, v222
	s_nop 0
	v_add_f32_e32 v222, 1.0, v222
	v_div_scale_f32 v223, s[10:11], v222, v222, v202
	v_rcp_f32_e32 v224, v223
	v_div_scale_f32 v225, vcc, v202, v222, v202
	v_fma_f32 v226, -v223, v224, 1.0
	v_fmac_f32_e32 v224, v226, v224
	v_mul_f32_e32 v226, v225, v224
	v_fma_f32 v227, -v223, v226, v225
	v_fmac_f32_e32 v226, v227, v224
	v_fma_f32 v223, -v223, v226, v225
	v_div_fmas_f32 v223, v223, v224, v226
	v_div_fixup_f32 v202, v223, v222, v202
	ds_write_b32 v160, v202 offset:4096
	s_waitcnt vmcnt(16)
	v_mul_f32_e32 v222, 0xbfb8aa3b, v203
	v_exp_f32_e32 v222, v222
	s_nop 0
	v_add_f32_e32 v222, 1.0, v222
	v_div_scale_f32 v223, s[10:11], v222, v222, v203
	v_rcp_f32_e32 v224, v223
	v_div_scale_f32 v225, vcc, v203, v222, v203
	v_fma_f32 v226, -v223, v224, 1.0
	v_fmac_f32_e32 v224, v226, v224
	v_mul_f32_e32 v226, v225, v224
	v_fma_f32 v227, -v223, v226, v225
	v_fmac_f32_e32 v226, v227, v224
	v_fma_f32 v223, -v223, v226, v225
	v_div_fmas_f32 v223, v223, v224, v226
	v_div_fixup_f32 v203, v223, v222, v203
	ds_write_b32 v160, v203 offset:6144
	s_waitcnt vmcnt(15)
	v_mul_f32_e32 v222, 0xbfb8aa3b, v204
	v_exp_f32_e32 v222, v222
	s_nop 0
	v_add_f32_e32 v222, 1.0, v222
	v_div_scale_f32 v223, s[10:11], v222, v222, v204
	v_rcp_f32_e32 v224, v223
	v_div_scale_f32 v225, vcc, v204, v222, v204
	v_fma_f32 v226, -v223, v224, 1.0
	v_fmac_f32_e32 v224, v226, v224
	v_mul_f32_e32 v226, v225, v224
	v_fma_f32 v227, -v223, v226, v225
	v_fmac_f32_e32 v226, v227, v224
	v_fma_f32 v223, -v223, v226, v225
	v_div_fmas_f32 v223, v223, v224, v226
	v_div_fixup_f32 v204, v223, v222, v204
	ds_write_b32 v160, v204 offset:8192
	s_waitcnt vmcnt(14)
	v_mul_f32_e32 v222, 0xbfb8aa3b, v205
	v_exp_f32_e32 v222, v222
	s_nop 0
	v_add_f32_e32 v222, 1.0, v222
	v_div_scale_f32 v223, s[10:11], v222, v222, v205
	v_rcp_f32_e32 v224, v223
	v_div_scale_f32 v225, vcc, v205, v222, v205
	v_fma_f32 v226, -v223, v224, 1.0
	v_fmac_f32_e32 v224, v226, v224
	v_mul_f32_e32 v226, v225, v224
	v_fma_f32 v227, -v223, v226, v225
	v_fmac_f32_e32 v226, v227, v224
	v_fma_f32 v223, -v223, v226, v225
	v_div_fmas_f32 v223, v223, v224, v226
	v_div_fixup_f32 v205, v223, v222, v205
	ds_write_b32 v160, v205 offset:10240
	s_waitcnt vmcnt(13)
	v_mul_f32_e32 v222, 0xbfb8aa3b, v206
	v_exp_f32_e32 v222, v222
	s_nop 0
	v_add_f32_e32 v222, 1.0, v222
	v_div_scale_f32 v223, s[10:11], v222, v222, v206
	v_rcp_f32_e32 v224, v223
	v_div_scale_f32 v225, vcc, v206, v222, v206
	v_fma_f32 v226, -v223, v224, 1.0
	v_fmac_f32_e32 v224, v226, v224
	v_mul_f32_e32 v226, v225, v224
	v_fma_f32 v227, -v223, v226, v225
	v_fmac_f32_e32 v226, v227, v224
	v_fma_f32 v223, -v223, v226, v225
	v_div_fmas_f32 v223, v223, v224, v226
	v_div_fixup_f32 v206, v223, v222, v206
	ds_write_b32 v160, v206 offset:12288
	s_waitcnt vmcnt(12)
; __device__ __forceinline__ float siluf_(float x) { return x / (1.f + __expf(-x)); }
; __device__ __forceinline__ void phase_mod(const Params& p, unsigned char* lds, const int layer, const int wb0, const int nwb) {
;     ...
;     for (int e = tid; e < 5 * D; e += 512) { const int r = e / D, k = e % D; const float v = r < 4 ? p.c[r * D + k] : p.c_ctx[k]; sc[e] = siluf_(v); }
	v_mul_f32_e32 v222, 0xbfb8aa3b, v207
	v_exp_f32_e32 v222, v222
	s_nop 0
	v_add_f32_e32 v222, 1.0, v222
	v_div_scale_f32 v223, s[10:11], v222, v222, v207
	v_rcp_f32_e32 v224, v223
	v_div_scale_f32 v225, vcc, v207, v222, v207
	v_fma_f32 v226, -v223, v224, 1.0
	v_fmac_f32_e32 v224, v226, v224
	v_mul_f32_e32 v226, v225, v224
	v_fma_f32 v227, -v223, v226, v225
	v_fmac_f32_e32 v226, v227, v224
	v_fma_f32 v223, -v223, v226, v225
	v_div_fmas_f32 v223, v223, v224, v226
	v_div_fixup_f32 v207, v223, v222, v207
	ds_write_b32 v160, v207 offset:14336
	s_waitcnt vmcnt(11)
	v_mul_f32_e32 v222, 0xbfb8aa3b, v208
	v_exp_f32_e32 v222, v222
	s_nop 0
	v_add_f32_e32 v222, 1.0, v222
	v_div_scale_f32 v223, s[10:11], v222, v222, v208
	v_rcp_f32_e32 v224, v223
	v_div_scale_f32 v225, vcc, v208, v222, v208
	v_fma_f32 v226, -v223, v224, 1.0
	v_fmac_f32_e32 v224, v226, v224
	v_mul_f32_e32 v226, v225, v224
	v_fma_f32 v227, -v223, v226, v225
	v_fmac_f32_e32 v226, v227, v224
	v_fma_f32 v223, -v223, v226, v225
	v_div_fmas_f32 v223, v223, v224, v226
	v_div_fixup_f32 v208, v223, v222, v208
	ds_write_b32 v160, v208 offset:16384
	s_waitcnt vmcnt(10)
	v_mul_f32_e32 v222, 0xbfb8aa3b, v209
	v_exp_f32_e32 v222, v222
	s_nop 0
	v_add_f32_e32 v222, 1.0, v222
	v_div_scale_f32 v223, s[10:11], v222, v222, v209
	v_rcp_f32_e32 v224, v223
	v_div_scale_f32 v225, vcc, v209, v222, v209
	v_fma_f32 v226, -v223, v224, 1.0
	v_fmac_f32_e32 v224, v226, v224
	v_mul_f32_e32 v226, v225, v224
	v_fma_f32 v227, -v223, v226, v225
	v_fmac_f32_e32 v226, v227, v224
	v_fma_f32 v223, -v223, v226, v225
	v_div_fmas_f32 v223, v223, v224, v226
	v_div_fixup_f32 v209, v223, v222, v209
	ds_write_b32 v160, v209 offset:18432
	s_waitcnt vmcnt(9)
	v_mul_f32_e32 v222, 0xbfb8aa3b, v210
	v_exp_f32_e32 v222, v222
	s_nop 0
	v_add_f32_e32 v222, 1.0, v222
	v_div_scale_f32 v223, s[10:11], v222, v222, v210
	v_rcp_f32_e32 v224, v223
	v_div_scale_f32 v225, vcc, v210, v222, v210
	v_fma_f32 v226, -v223, v224, 1.0
	v_fmac_f32_e32 v224, v226, v224
	v_mul_f32_e32 v226, v225, v224
	v_fma_f32 v227, -v223, v226, v225
	v_fmac_f32_e32 v226, v227, v224
	v_fma_f32 v223, -v223, v226, v225
	v_div_fmas_f32 v223, v223, v224, v226
	v_div_fixup_f32 v210, v223, v222, v210
	ds_write_b32 v160, v210 offset:20480
	s_waitcnt vmcnt(8)
	v_mul_f32_e32 v222, 0xbfb8aa3b, v211
	v_exp_f32_e32 v222, v222
	s_nop 0
	v_add_f32_e32 v222, 1.0, v222
	v_div_scale_f32 v223, s[10:11], v222, v222, v211
	v_rcp_f32_e32 v224, v223
	v_div_scale_f32 v225, vcc, v211, v222, v211
	v_fma_f32 v226, -v223, v224, 1.0
	v_fmac_f32_e32 v224, v226, v224
	v_mul_f32_e32 v226, v225, v224
	v_fma_f32 v227, -v223, v226, v225
	v_fmac_f32_e32 v226, v227, v224
	v_fma_f32 v223, -v223, v226, v225
	v_div_fmas_f32 v223, v223, v224, v226
	v_div_fixup_f32 v211, v223, v222, v211
	ds_write_b32 v160, v211 offset:22528
	s_waitcnt vmcnt(7)
	v_mul_f32_e32 v222, 0xbfb8aa3b, v212
	v_exp_f32_e32 v222, v222
	s_nop 0
	v_add_f32_e32 v222, 1.0, v222
	v_div_scale_f32 v223, s[10:11], v222, v222, v212
	v_rcp_f32_e32 v224, v223
	v_div_scale_f32 v225, vcc, v212, v222, v212
	v_fma_f32 v226, -v223, v224, 1.0
	v_fmac_f32_e32 v224, v226, v224
	v_mul_f32_e32 v226, v225, v224
	v_fma_f32 v227, -v223, v226, v225
	v_fmac_f32_e32 v226, v227, v224
	v_fma_f32 v223, -v223, v226, v225
	v_div_fmas_f32 v223, v223, v224, v226
	v_div_fixup_f32 v212, v223, v222, v212
	ds_write_b32 v160, v212 offset:24576
	s_waitcnt vmcnt(6)
	v_mul_f32_e32 v222, 0xbfb8aa3b, v213
	v_exp_f32_e32 v222, v222
	s_nop 0
	v_add_f32_e32 v222, 1.0, v222
	v_div_scale_f32 v223, s[10:11], v222, v222, v213
	v_rcp_f32_e32 v224, v223
	v_div_scale_f32 v225, vcc, v213, v222, v213
	v_fma_f32 v226, -v223, v224, 1.0
	v_fmac_f32_e32 v224, v226, v224
	v_mul_f32_e32 v226, v225, v224
	v_fma_f32 v227, -v223, v226, v225
	v_fmac_f32_e32 v226, v227, v224
	v_fma_f32 v223, -v223, v226, v225
	v_div_fmas_f32 v223, v223, v224, v226
	v_div_fixup_f32 v213, v223, v222, v213
	ds_write_b32 v160, v213 offset:26624
	s_waitcnt vmcnt(5)
	v_mul_f32_e32 v222, 0xbfb8aa3b, v214
	v_exp_f32_e32 v222, v222
	s_nop 0
	v_add_f32_e32 v222, 1.0, v222
	v_div_scale_f32 v223, s[10:11], v222, v222, v214
	v_rcp_f32_e32 v224, v223
	v_div_scale_f32 v225, vcc, v214, v222, v214
	v_fma_f32 v226, -v223, v224, 1.0
	v_fmac_f32_e32 v224, v226, v224
	v_mul_f32_e32 v226, v225, v224
	v_fma_f32 v227, -v223, v226, v225
	v_fmac_f32_e32 v226, v227, v224
	v_fma_f32 v223, -v223, v226, v225
	v_div_fmas_f32 v223, v223, v224, v226
	v_div_fixup_f32 v214, v223, v222, v214
	ds_write_b32 v160, v214 offset:28672
	s_waitcnt vmcnt(4)
; __device__ __forceinline__ float siluf_(float x) { return x / (1.f + __expf(-x)); }
; __device__ __forceinline__ void phase_mod(const Params& p, unsigned char* lds, const int layer, const int wb0, const int nwb) {
;     ...
;     for (int e = tid; e < 5 * D; e += 512) { const int r = e / D, k = e % D; const float v = r < 4 ? p.c[r * D + k] : p.c_ctx[k]; sc[e] = siluf_(v); }
;     __syncthreads();
;     for (int it = (int)blockIdx.x - wb0; it < 256; it += nwb) {
;         const int l = layer, n0 = it * 48;
;         const int kg = tid / 12, cg_ = tid % 12;
;         float acc[5][4];
; #pragma unroll
;         for (int r = 0; r < 5; ++r)
; #pragma unroll
;             for (int j = 0; j < 4; ++j) acc[r][j] = 0.f;
;         if (kg < 42) {
;             const float* wp = p.mod_w + (size_t)l * D * (6 * D) + n0 + 4 * cg_;
; #pragma unroll 4
;             for (int k = kg; k < D; k += 42) {
;                 const f32x4 w = *(const f32x4*)(wp + (size_t)k * (6 * D));
	v_mul_f32_e32 v222, 0xbfb8aa3b, v215
	v_exp_f32_e32 v222, v222
	s_nop 0
	v_add_f32_e32 v222, 1.0, v222
	v_div_scale_f32 v223, s[10:11], v222, v222, v215
	v_rcp_f32_e32 v224, v223
	v_div_scale_f32 v225, vcc, v215, v222, v215
	v_fma_f32 v226, -v223, v224, 1.0
	v_fmac_f32_e32 v224, v226, v224
	v_mul_f32_e32 v226, v225, v224
	v_fma_f32 v227, -v223, v226, v225
	v_fmac_f32_e32 v226, v227, v224
	v_fma_f32 v223, -v223, v226, v225
	v_div_fmas_f32 v223, v223, v224, v226
	v_div_fixup_f32 v215, v223, v222, v215
	ds_write_b32 v160, v215 offset:30720
	s_waitcnt vmcnt(3)
	v_mul_f32_e32 v222, 0xbfb8aa3b, v216
	v_exp_f32_e32 v222, v222
	s_nop 0
	v_add_f32_e32 v222, 1.0, v222
	v_div_scale_f32 v223, s[10:11], v222, v222, v216
	v_rcp_f32_e32 v224, v223
	v_div_scale_f32 v225, vcc, v216, v222, v216
	v_fma_f32 v226, -v223, v224, 1.0
	v_fmac_f32_e32 v224, v226, v224
	v_mul_f32_e32 v226, v225, v224
	v_fma_f32 v227, -v223, v226, v225
	v_fmac_f32_e32 v226, v227, v224
	v_fma_f32 v223, -v223, v226, v225
	v_div_fmas_f32 v223, v223, v224, v226
	v_div_fixup_f32 v216, v223, v222, v216
	ds_write_b32 v160, v216 offset:32768
	s_waitcnt vmcnt(2)
	v_mul_f32_e32 v222, 0xbfb8aa3b, v217
	v_exp_f32_e32 v222, v222
	s_nop 0
	v_add_f32_e32 v222, 1.0, v222
	v_div_scale_f32 v223, s[10:11], v222, v222, v217
	v_rcp_f32_e32 v224, v223
	v_div_scale_f32 v225, vcc, v217, v222, v217
	v_fma_f32 v226, -v223, v224, 1.0
	v_fmac_f32_e32 v224, v226, v224
	v_mul_f32_e32 v226, v225, v224
	v_fma_f32 v227, -v223, v226, v225
	v_fmac_f32_e32 v226, v227, v224
	v_fma_f32 v223, -v223, v226, v225
	v_div_fmas_f32 v223, v223, v224, v226
	v_div_fixup_f32 v217, v223, v222, v217
	ds_write_b32 v160, v217 offset:34816
	s_waitcnt vmcnt(1)
	v_mul_f32_e32 v222, 0xbfb8aa3b, v218
	v_exp_f32_e32 v222, v222
	s_nop 0
	v_add_f32_e32 v222, 1.0, v222
	v_div_scale_f32 v223, s[10:11], v222, v222, v218
	v_rcp_f32_e32 v224, v223
	v_div_scale_f32 v225, vcc, v218, v222, v218
	v_fma_f32 v226, -v223, v224, 1.0
	v_fmac_f32_e32 v224, v226, v224
	v_mul_f32_e32 v226, v225, v224
	v_fma_f32 v227, -v223, v226, v225
	v_fmac_f32_e32 v226, v227, v224
	v_fma_f32 v223, -v223, v226, v225
	v_div_fmas_f32 v223, v223, v224, v226
	v_div_fixup_f32 v218, v223, v222, v218
	ds_write_b32 v160, v218 offset:36864
	s_waitcnt vmcnt(0)
	v_mul_f32_e32 v222, 0xbfb8aa3b, v219
	v_exp_f32_e32 v222, v222
	s_nop 0
	v_add_f32_e32 v222, 1.0, v222
	v_div_scale_f32 v223, s[10:11], v222, v222, v219
	v_rcp_f32_e32 v224, v223
	v_div_scale_f32 v225, vcc, v219, v222, v219
	v_fma_f32 v226, -v223, v224, 1.0
	v_fmac_f32_e32 v224, v226, v224
	v_mul_f32_e32 v226, v225, v224
	v_fma_f32 v227, -v223, v226, v225
	v_fmac_f32_e32 v226, v227, v224
	v_fma_f32 v223, -v223, v226, v225
	v_div_fmas_f32 v223, v223, v224, v226
	v_div_fixup_f32 v219, v223, v222, v219
	ds_write_b32 v160, v219 offset:38912
	s_or_b64 exec, exec, s[4:5]
	v_and_b32_e32 v0, 31, v162
	v_cvt_f32_ubyte0_e32 v33, v0
	v_mul_f32_e32 v0, 0xbed49a78, v33
	s_mov_b32 s4, 0xc2fc0000
	s_cmpk_gt_i32 s92, 0xff
	v_cmp_gt_f32_e32 vcc, s4, v0
	s_waitcnt lgkmcnt(0)
	s_barrier
	s_cbranch_scc1 .LBB0_33
	v_mul_lo_u16_e32 v0, 12, v32
	v_sub_u16_e32 v2, v162, v0
	v_mul_lo_u16_e32 v0, 48, v7
	v_sub_u16_e32 v34, v162, v0
	v_lshlrev_b32_e32 v20, 2, v6
	v_mov_b32_e32 v21, 0
	v_mov_b32_e32 v3, 2
	v_lshl_add_u64 v[0:1], s[90:91], 0, v[20:21]
	v_lshlrev_b32_sdwa v20, v3, v34 dst_sel:DWORD dst_unused:UNUSED_PAD src0_sel:DWORD src1_sel:BYTE_0
	v_lshl_add_u64 v[22:23], v[0:1], 0, v[20:21]
	v_lshlrev_b16_e32 v0, 2, v2
	v_lshlrev_b32_e32 v0, 2, v0
	v_mov_b32_e32 v1, v21
	v_lshl_add_u64 v[24:25], s[44:45], 0, v[0:1]
	v_sub_u32_e32 v1, 0x7d5, v32
	s_mov_b32 s8, 0x6186187
	v_mul_hi_u32 v1, v1, s8
	s_movk_i32 s4, 0x1f8
	s_movk_i32 s6, 0xf0
	v_add_u32_e32 v0, 0, v0
	v_add3_u32 v35, 0, v20, v5
	v_and_b32_e32 v37, 3, v1
	v_lshlrev_b32_e32 v38, 2, v32
	v_cmp_gt_u32_e64 s[4:5], s4, v162
	v_cmp_gt_u32_e64 s[6:7], s6, v162
	v_add_u32_e32 v36, 0xa000, v35
	v_cmp_ne_u32_e64 s[8:9], 2, v37
	v_add_u32_e32 v39, 0, v38
	s_movk_i32 s24, 0x3000
	v_mul_u32_u24_e32 v40, 0x3000, v32
	s_mul_i32 s12, s92, 48
	s_mul_i32 s25, s82, 48
	s_mov_b64 s[14:15], 0x7e0000
	s_movk_i32 s26, 0x757
	v_add_u32_e32 v41, v0, v4
	s_mov_b32 s27, s92
	s_branch .LBB0_23

; __device__ __forceinline__ float siluf_(float x) { return x / (1.f + __expf(-x)); }
; __device__ __forceinline__ void phase_mod(const Params& p, unsigned char* lds, const int layer, const int wb0, const int nwb) {
;     const int tid = threadIdx.x;
;     float* sc = (float*)lds;
;     float* red = (float*)(lds + 40960);
;     float* modv = (float*)(p.ws + WS_MODV);
;     __syncthreads();
;     for (int e = tid; e < 5 * D; e += 512) { const int r = e / D, k = e % D; const float v = r < 4 ? p.c[r * D + k] : p.c_ctx[k]; sc[e] = siluf_(v); }
.Lmod_all:
.LBB0_586:
	s_or_b64 exec, exec, s[0:1]
	v_readlane_b32 s52, v241, 1
	v_mov_b32_e32 v65, 0
	v_readlane_b32 s54, v241, 3
	v_readlane_b32 s55, v241, 4
	v_readlane_b32 s58, v241, 7
	v_readlane_b32 s59, v241, 8
	v_lshl_add_u64 v[0:1], s[54:55], 0, v[64:65]
	s_mov_b64 s[0:1], 0
	s_movk_i32 s4, 0x2000
	s_mov_b64 s[2:3], 0x800
	s_movk_i32 s5, 0x25ff
	v_mov_b32_e32 v2, v162
	s_barrier
	s_barrier
	s_mov_b32 s10, 0
	s_mov_b32 s18, s92
	s_mov_b32 s19, s82
	v_readlane_b32 s53, v241, 2
	v_readlane_b32 s56, v241, 5
	v_readlane_b32 s57, v241, 6
	v_readlane_b32 s60, v241, 9
	v_readlane_b32 s61, v241, 10
	v_readlane_b32 s62, v241, 11
	v_readlane_b32 s63, v241, 12
	v_readlane_b32 s64, v241, 13
	v_readlane_b32 s65, v241, 14
	v_readlane_b32 s66, v241, 15
	v_readlane_b32 s67, v241, 16
	v_mov_b32_e32 v220, v64
	global_load_dword v200, v220, s[54:55]
	global_load_dword v201, v220, s[54:55] offset:2048
	v_add_u32_e32 v220, 0x1000, v220
	global_load_dword v202, v220, s[54:55]
	global_load_dword v203, v220, s[54:55] offset:2048
	v_add_u32_e32 v220, 0x1000, v220
	global_load_dword v204, v220, s[54:55]
	global_load_dword v205, v220, s[54:55] offset:2048
	v_add_u32_e32 v220, 0x1000, v220
	global_load_dword v206, v220, s[54:55]
	global_load_dword v207, v220, s[54:55] offset:2048
	v_add_u32_e32 v220, 0x1000, v220
	global_load_dword v208, v220, s[54:55]
	global_load_dword v209, v220, s[54:55] offset:2048
	v_add_u32_e32 v220, 0x1000, v220
	global_load_dword v210, v220, s[54:55]
	global_load_dword v211, v220, s[54:55] offset:2048
	v_add_u32_e32 v220, 0x1000, v220
	global_load_dword v212, v220, s[54:55]
	global_load_dword v213, v220, s[54:55] offset:2048
	v_add_u32_e32 v220, 0x1000, v220
	global_load_dword v214, v220, s[54:55]
	global_load_dword v215, v220, s[54:55] offset:2048
	global_load_dword v216, v64, s[58:59]
	global_load_dword v217, v64, s[58:59] offset:2048
	v_add_u32_e32 v220, 0x1000, v64
	global_load_dword v218, v220, s[58:59]
	global_load_dword v219, v220, s[58:59] offset:2048
	s_waitcnt vmcnt(19)
	v_mul_f32_e32 v222, 0xbfb8aa3b, v200
	v_exp_f32_e32 v222, v222
	s_nop 0
	v_add_f32_e32 v222, 1.0, v222
	v_div_scale_f32 v223, s[6:7], v222, v222, v200
	v_rcp_f32_e32 v224, v223
	v_div_scale_f32 v225, vcc, v200, v222, v200
	v_fma_f32 v226, -v223, v224, 1.0
	v_fmac_f32_e32 v224, v226, v224
	v_mul_f32_e32 v226, v225, v224
	v_fma_f32 v227, -v223, v226, v225
	v_fmac_f32_e32 v226, v227, v224
	v_fma_f32 v223, -v223, v226, v225
	v_div_fmas_f32 v223, v223, v224, v226
	v_div_fixup_f32 v200, v223, v222, v200
	ds_write_b32 v64, v200
	s_waitcnt vmcnt(18)
	v_mul_f32_e32 v222, 0xbfb8aa3b, v201
	v_exp_f32_e32 v222, v222
	s_nop 0
	v_add_f32_e32 v222, 1.0, v222
	v_div_scale_f32 v223, s[6:7], v222, v222, v201
	v_rcp_f32_e32 v224, v223
	v_div_scale_f32 v225, vcc, v201, v222, v201
	v_fma_f32 v226, -v223, v224, 1.0
	v_fmac_f32_e32 v224, v226, v224
	v_mul_f32_e32 v226, v225, v224
	v_fma_f32 v227, -v223, v226, v225
	v_fmac_f32_e32 v226, v227, v224
	v_fma_f32 v223, -v223, v226, v225
	v_div_fmas_f32 v223, v223, v224, v226
	v_div_fixup_f32 v201, v223, v222, v201
	ds_write_b32 v64, v201 offset:2048
	s_waitcnt vmcnt(17)
	v_mul_f32_e32 v222, 0xbfb8aa3b, v202
	v_exp_f32_e32 v222, v222
	s_nop 0
	v_add_f32_e32 v222, 1.0, v222
	v_div_scale_f32 v223, s[6:7], v222, v222, v202
	v_rcp_f32_e32 v224, v223
	v_div_scale_f32 v225, vcc, v202, v222, v202
	v_fma_f32 v226, -v223, v224, 1.0
	v_fmac_f32_e32 v224, v226, v224
	v_mul_f32_e32 v226, v225, v224
	v_fma_f32 v227, -v223, v226, v225
	v_fmac_f32_e32 v226, v227, v224
	v_fma_f32 v223, -v223, v226, v225
	v_div_fmas_f32 v223, v223, v224, v226
	v_div_fixup_f32 v202, v223, v222, v202
	ds_write_b32 v64, v202 offset:4096
	s_waitcnt vmcnt(16)
	v_mul_f32_e32 v222, 0xbfb8aa3b, v203
	v_exp_f32_e32 v222, v222
	s_nop 0
	v_add_f32_e32 v222, 1.0, v222
	v_div_scale_f32 v223, s[6:7], v222, v222, v203
	v_rcp_f32_e32 v224, v223
	v_div_scale_f32 v225, vcc, v203, v222, v203
	v_fma_f32 v226, -v223, v224, 1.0
	v_fmac_f32_e32 v224, v226, v224
	v_mul_f32_e32 v226, v225, v224
	v_fma_f32 v227, -v223, v226, v225
	v_fmac_f32_e32 v226, v227, v224
	v_fma_f32 v223, -v223, v226, v225
	v_div_fmas_f32 v223, v223, v224, v226
	v_div_fixup_f32 v203, v223, v222, v203
	ds_write_b32 v64, v203 offset:6144
	s_waitcnt vmcnt(15)
	v_mul_f32_e32 v222, 0xbfb8aa3b, v204
	v_exp_f32_e32 v222, v222
	s_nop 0
	v_add_f32_e32 v222, 1.0, v222
	v_div_scale_f32 v223, s[6:7], v222, v222, v204
	v_rcp_f32_e32 v224, v223
	v_div_scale_f32 v225, vcc, v204, v222, v204
	v_fma_f32 v226, -v223, v224, 1.0
	v_fmac_f32_e32 v224, v226, v224
	v_mul_f32_e32 v226, v225, v224
	v_fma_f32 v227, -v223, v226, v225
	v_fmac_f32_e32 v226, v227, v224
	v_fma_f32 v223, -v223, v226, v225
	v_div_fmas_f32 v223, v223, v224, v226
	v_div_fixup_f32 v204, v223, v222, v204
	ds_write_b32 v64, v204 offset:8192
	s_waitcnt vmcnt(14)
	v_mul_f32_e32 v222, 0xbfb8aa3b, v205
	v_exp_f32_e32 v222, v222
	s_nop 0
	v_add_f32_e32 v222, 1.0, v222
	v_div_scale_f32 v223, s[6:7], v222, v222, v205
	v_rcp_f32_e32 v224, v223
	v_div_scale_f32 v225, vcc, v205, v222, v205
	v_fma_f32 v226, -v223, v224, 1.0
	v_fmac_f32_e32 v224, v226, v224
	v_mul_f32_e32 v226, v225, v224
	v_fma_f32 v227, -v223, v226, v225
	v_fmac_f32_e32 v226, v227, v224
	v_fma_f32 v223, -v223, v226, v225
	v_div_fmas_f32 v223, v223, v224, v226
	v_div_fixup_f32 v205, v223, v222, v205
	ds_write_b32 v64, v205 offset:10240
	s_waitcnt vmcnt(13)
; __device__ __forceinline__ float siluf_(float x) { return x / (1.f + __expf(-x)); }
; __device__ __forceinline__ void phase_mod(const Params& p, unsigned char* lds, const int layer, const int wb0, const int nwb) {
;     ...
;     for (int e = tid; e < 5 * D; e += 512) { const int r = e / D, k = e % D; const float v = r < 4 ? p.c[r * D + k] : p.c_ctx[k]; sc[e] = siluf_(v); }
	v_mul_f32_e32 v222, 0xbfb8aa3b, v206
	v_exp_f32_e32 v222, v222
	s_nop 0
	v_add_f32_e32 v222, 1.0, v222
	v_div_scale_f32 v223, s[6:7], v222, v222, v206
	v_rcp_f32_e32 v224, v223
	v_div_scale_f32 v225, vcc, v206, v222, v206
	v_fma_f32 v226, -v223, v224, 1.0
	v_fmac_f32_e32 v224, v226, v224
	v_mul_f32_e32 v226, v225, v224
	v_fma_f32 v227, -v223, v226, v225
	v_fmac_f32_e32 v226, v227, v224
	v_fma_f32 v223, -v223, v226, v225
	v_div_fmas_f32 v223, v223, v224, v226
	v_div_fixup_f32 v206, v223, v222, v206
	ds_write_b32 v64, v206 offset:12288
	s_waitcnt vmcnt(12)
	v_mul_f32_e32 v222, 0xbfb8aa3b, v207
	v_exp_f32_e32 v222, v222
	s_nop 0
	v_add_f32_e32 v222, 1.0, v222
	v_div_scale_f32 v223, s[6:7], v222, v222, v207
	v_rcp_f32_e32 v224, v223
	v_div_scale_f32 v225, vcc, v207, v222, v207
	v_fma_f32 v226, -v223, v224, 1.0
	v_fmac_f32_e32 v224, v226, v224
	v_mul_f32_e32 v226, v225, v224
	v_fma_f32 v227, -v223, v226, v225
	v_fmac_f32_e32 v226, v227, v224
	v_fma_f32 v223, -v223, v226, v225
	v_div_fmas_f32 v223, v223, v224, v226
	v_div_fixup_f32 v207, v223, v222, v207
	ds_write_b32 v64, v207 offset:14336
	s_waitcnt vmcnt(11)
	v_mul_f32_e32 v222, 0xbfb8aa3b, v208
	v_exp_f32_e32 v222, v222
	s_nop 0
	v_add_f32_e32 v222, 1.0, v222
	v_div_scale_f32 v223, s[6:7], v222, v222, v208
	v_rcp_f32_e32 v224, v223
	v_div_scale_f32 v225, vcc, v208, v222, v208
	v_fma_f32 v226, -v223, v224, 1.0
	v_fmac_f32_e32 v224, v226, v224
	v_mul_f32_e32 v226, v225, v224
	v_fma_f32 v227, -v223, v226, v225
	v_fmac_f32_e32 v226, v227, v224
	v_fma_f32 v223, -v223, v226, v225
	v_div_fmas_f32 v223, v223, v224, v226
	v_div_fixup_f32 v208, v223, v222, v208
	ds_write_b32 v64, v208 offset:16384
	s_waitcnt vmcnt(10)
	v_mul_f32_e32 v222, 0xbfb8aa3b, v209
	v_exp_f32_e32 v222, v222
	s_nop 0
	v_add_f32_e32 v222, 1.0, v222
	v_div_scale_f32 v223, s[6:7], v222, v222, v209
	v_rcp_f32_e32 v224, v223
	v_div_scale_f32 v225, vcc, v209, v222, v209
	v_fma_f32 v226, -v223, v224, 1.0
	v_fmac_f32_e32 v224, v226, v224
	v_mul_f32_e32 v226, v225, v224
	v_fma_f32 v227, -v223, v226, v225
	v_fmac_f32_e32 v226, v227, v224
	v_fma_f32 v223, -v223, v226, v225
	v_div_fmas_f32 v223, v223, v224, v226
	v_div_fixup_f32 v209, v223, v222, v209
	ds_write_b32 v64, v209 offset:18432
	s_waitcnt vmcnt(9)
	v_mul_f32_e32 v222, 0xbfb8aa3b, v210
	v_exp_f32_e32 v222, v222
	s_nop 0
	v_add_f32_e32 v222, 1.0, v222
	v_div_scale_f32 v223, s[6:7], v222, v222, v210
	v_rcp_f32_e32 v224, v223
	v_div_scale_f32 v225, vcc, v210, v222, v210
	v_fma_f32 v226, -v223, v224, 1.0
	v_fmac_f32_e32 v224, v226, v224
	v_mul_f32_e32 v226, v225, v224
	v_fma_f32 v227, -v223, v226, v225
	v_fmac_f32_e32 v226, v227, v224
	v_fma_f32 v223, -v223, v226, v225
	v_div_fmas_f32 v223, v223, v224, v226
	v_div_fixup_f32 v210, v223, v222, v210
	ds_write_b32 v64, v210 offset:20480
	s_waitcnt vmcnt(8)
	v_mul_f32_e32 v222, 0xbfb8aa3b, v211
	v_exp_f32_e32 v222, v222
	s_nop 0
	v_add_f32_e32 v222, 1.0, v222
	v_div_scale_f32 v223, s[6:7], v222, v222, v211
	v_rcp_f32_e32 v224, v223
	v_div_scale_f32 v225, vcc, v211, v222, v211
	v_fma_f32 v226, -v223, v224, 1.0
	v_fmac_f32_e32 v224, v226, v224
	v_mul_f32_e32 v226, v225, v224
	v_fma_f32 v227, -v223, v226, v225
	v_fmac_f32_e32 v226, v227, v224
	v_fma_f32 v223, -v223, v226, v225
	v_div_fmas_f32 v223, v223, v224, v226
	v_div_fixup_f32 v211, v223, v222, v211
	ds_write_b32 v64, v211 offset:22528
	s_waitcnt vmcnt(7)
	v_mul_f32_e32 v222, 0xbfb8aa3b, v212
	v_exp_f32_e32 v222, v222
	s_nop 0
	v_add_f32_e32 v222, 1.0, v222
	v_div_scale_f32 v223, s[6:7], v222, v222, v212
	v_rcp_f32_e32 v224, v223
	v_div_scale_f32 v225, vcc, v212, v222, v212
	v_fma_f32 v226, -v223, v224, 1.0
	v_fmac_f32_e32 v224, v226, v224
	v_mul_f32_e32 v226, v225, v224
	v_fma_f32 v227, -v223, v226, v225
	v_fmac_f32_e32 v226, v227, v224
	v_fma_f32 v223, -v223, v226, v225
	v_div_fmas_f32 v223, v223, v224, v226
	v_div_fixup_f32 v212, v223, v222, v212
	ds_write_b32 v64, v212 offset:24576
	s_waitcnt vmcnt(6)
	v_mul_f32_e32 v222, 0xbfb8aa3b, v213
	v_exp_f32_e32 v222, v222
	s_nop 0
	v_add_f32_e32 v222, 1.0, v222
	v_div_scale_f32 v223, s[6:7], v222, v222, v213
	v_rcp_f32_e32 v224, v223
	v_div_scale_f32 v225, vcc, v213, v222, v213
	v_fma_f32 v226, -v223, v224, 1.0
	v_fmac_f32_e32 v224, v226, v224
	v_mul_f32_e32 v226, v225, v224
	v_fma_f32 v227, -v223, v226, v225
	v_fmac_f32_e32 v226, v227, v224
	v_fma_f32 v223, -v223, v226, v225
	v_div_fmas_f32 v223, v223, v224, v226
	v_div_fixup_f32 v213, v223, v222, v213
	ds_write_b32 v64, v213 offset:26624
	s_waitcnt vmcnt(5)
	v_mul_f32_e32 v222, 0xbfb8aa3b, v214
	v_exp_f32_e32 v222, v222
	s_nop 0
	v_add_f32_e32 v222, 1.0, v222
	v_div_scale_f32 v223, s[6:7], v222, v222, v214
	v_rcp_f32_e32 v224, v223
	v_div_scale_f32 v225, vcc, v214, v222, v214
	v_fma_f32 v226, -v223, v224, 1.0
	v_fmac_f32_e32 v224, v226, v224
	v_mul_f32_e32 v226, v225, v224
	v_fma_f32 v227, -v223, v226, v225
	v_fmac_f32_e32 v226, v227, v224
	v_fma_f32 v223, -v223, v226, v225
	v_div_fmas_f32 v223, v223, v224, v226
	v_div_fixup_f32 v214, v223, v222, v214
	ds_write_b32 v64, v214 offset:28672
	s_waitcnt vmcnt(4)
; __device__ __forceinline__ float siluf_(float x) { return x / (1.f + __expf(-x)); }
; __device__ __forceinline__ void phase_mod(const Params& p, unsigned char* lds, const int layer, const int wb0, const int nwb) {
;     ...
;     for (int e = tid; e < 5 * D; e += 512) { const int r = e / D, k = e % D; const float v = r < 4 ? p.c[r * D + k] : p.c_ctx[k]; sc[e] = siluf_(v); }
;     __syncthreads();
;     for (int it = (int)blockIdx.x - wb0; it < 256; it += nwb) {
;         const int l = layer, n0 = it * 48;
;         const int kg = tid / 12, cg_ = tid % 12;
;         float acc[5][4];
; #pragma unroll
;         for (int r = 0; r < 5; ++r)
; #pragma unroll
;             for (int j = 0; j < 4; ++j) acc[r][j] = 0.f;
;         if (kg < 42) {
;             const float* wp = p.mod_w + (size_t)l * D * (6 * D) + n0 + 4 * cg_;
; #pragma unroll 4
;             for (int k = kg; k < D; k += 42) {
;                 const f32x4 w = *(const f32x4*)(wp + (size_t)k * (6 * D));
	v_mul_f32_e32 v222, 0xbfb8aa3b, v215
	v_exp_f32_e32 v222, v222
	s_nop 0
	v_add_f32_e32 v222, 1.0, v222
	v_div_scale_f32 v223, s[6:7], v222, v222, v215
	v_rcp_f32_e32 v224, v223
	v_div_scale_f32 v225, vcc, v215, v222, v215
	v_fma_f32 v226, -v223, v224, 1.0
	v_fmac_f32_e32 v224, v226, v224
	v_mul_f32_e32 v226, v225, v224
	v_fma_f32 v227, -v223, v226, v225
	v_fmac_f32_e32 v226, v227, v224
	v_fma_f32 v223, -v223, v226, v225
	v_div_fmas_f32 v223, v223, v224, v226
	v_div_fixup_f32 v215, v223, v222, v215
	ds_write_b32 v64, v215 offset:30720
	s_waitcnt vmcnt(3)
	v_mul_f32_e32 v222, 0xbfb8aa3b, v216
	v_exp_f32_e32 v222, v222
	s_nop 0
	v_add_f32_e32 v222, 1.0, v222
	v_div_scale_f32 v223, s[6:7], v222, v222, v216
	v_rcp_f32_e32 v224, v223
	v_div_scale_f32 v225, vcc, v216, v222, v216
	v_fma_f32 v226, -v223, v224, 1.0
	v_fmac_f32_e32 v224, v226, v224
	v_mul_f32_e32 v226, v225, v224
	v_fma_f32 v227, -v223, v226, v225
	v_fmac_f32_e32 v226, v227, v224
	v_fma_f32 v223, -v223, v226, v225
	v_div_fmas_f32 v223, v223, v224, v226
	v_div_fixup_f32 v216, v223, v222, v216
	ds_write_b32 v64, v216 offset:32768
	s_waitcnt vmcnt(2)
	v_mul_f32_e32 v222, 0xbfb8aa3b, v217
	v_exp_f32_e32 v222, v222
	s_nop 0
	v_add_f32_e32 v222, 1.0, v222
	v_div_scale_f32 v223, s[6:7], v222, v222, v217
	v_rcp_f32_e32 v224, v223
	v_div_scale_f32 v225, vcc, v217, v222, v217
	v_fma_f32 v226, -v223, v224, 1.0
	v_fmac_f32_e32 v224, v226, v224
	v_mul_f32_e32 v226, v225, v224
	v_fma_f32 v227, -v223, v226, v225
	v_fmac_f32_e32 v226, v227, v224
	v_fma_f32 v223, -v223, v226, v225
	v_div_fmas_f32 v223, v223, v224, v226
	v_div_fixup_f32 v217, v223, v222, v217
	ds_write_b32 v64, v217 offset:34816
	s_waitcnt vmcnt(1)
	v_mul_f32_e32 v222, 0xbfb8aa3b, v218
	v_exp_f32_e32 v222, v222
	s_nop 0
	v_add_f32_e32 v222, 1.0, v222
	v_div_scale_f32 v223, s[6:7], v222, v222, v218
	v_rcp_f32_e32 v224, v223
	v_div_scale_f32 v225, vcc, v218, v222, v218
	v_fma_f32 v226, -v223, v224, 1.0
	v_fmac_f32_e32 v224, v226, v224
	v_mul_f32_e32 v226, v225, v224
	v_fma_f32 v227, -v223, v226, v225
	v_fmac_f32_e32 v226, v227, v224
	v_fma_f32 v223, -v223, v226, v225
	v_div_fmas_f32 v223, v223, v224, v226
	v_div_fixup_f32 v218, v223, v222, v218
	ds_write_b32 v64, v218 offset:36864
	s_waitcnt vmcnt(0)
	v_mul_f32_e32 v222, 0xbfb8aa3b, v219
	v_exp_f32_e32 v222, v222
	s_nop 0
	v_add_f32_e32 v222, 1.0, v222
	v_div_scale_f32 v223, s[6:7], v222, v222, v219
	v_rcp_f32_e32 v224, v223
	v_div_scale_f32 v225, vcc, v219, v222, v219
	v_fma_f32 v226, -v223, v224, 1.0
	v_fmac_f32_e32 v224, v226, v224
	v_mul_f32_e32 v226, v225, v224
	v_fma_f32 v227, -v223, v226, v225
	v_fmac_f32_e32 v226, v227, v224
	v_fma_f32 v223, -v223, v226, v225
	v_div_fmas_f32 v223, v223, v224, v226
	v_div_fixup_f32 v219, v223, v222, v219
	ds_write_b32 v64, v219 offset:38912
	s_or_b64 exec, exec, s[0:1]
	s_cmpk_gt_i32 s18, 0xff
	s_waitcnt lgkmcnt(0)
	s_barrier
	s_cbranch_scc1 .LBB0_601
	v_mul_lo_u16_e32 v0, 12, v79
	v_sub_u16_e32 v2, v162, v0
	v_mul_lo_u16_e32 v0, 48, v103
	v_sub_u16_e32 v3, v162, v0
	v_lshlrev_b32_e32 v20, 2, v102
	v_mov_b32_e32 v21, 0
	v_mov_b32_e32 v4, 2
	v_lshl_add_u64 v[0:1], s[90:91], 0, v[20:21]
	v_lshlrev_b32_sdwa v20, v4, v3 dst_sel:DWORD dst_unused:UNUSED_PAD src0_sel:DWORD src1_sel:BYTE_0
	v_lshl_add_u64 v[0:1], v[0:1], 0, v[20:21]
	s_mov_b64 s[2:3], 0x3c000
	v_lshl_add_u64 v[22:23], v[0:1], 0, s[2:3]
	v_lshlrev_b16_e32 v0, 2, v2
	v_readlane_b32 s52, v241, 1
	s_movk_i32 s20, 0x3000
	v_lshlrev_b32_e32 v0, 2, v0
	v_mov_b32_e32 v1, v21
	v_readlane_b32 s60, v241, 9
	v_readlane_b32 s61, v241, 10
	v_or_b32_sdwa v32, v3, s20 dst_sel:DWORD dst_unused:UNUSED_PAD src0_sel:BYTE_0 src1_sel:DWORD
	s_mov_b64 s[2:3], 0x6000000
	v_lshl_add_u64 v[2:3], s[60:61], 0, v[0:1]
	v_lshl_add_u64 v[24:25], v[2:3], 0, s[2:3]
	v_sub_u32_e32 v1, 0x7d5, v79
	s_mov_b32 s2, 0x6186187
	s_movk_i32 s0, 0x1f8
	v_mul_hi_u32 v1, v1, s2
	v_cmp_gt_u32_e32 vcc, s0, v162
	s_movk_i32 s0, 0xf0
	v_add_u32_e32 v0, 0, v0
	v_add3_u32 v33, 0, v20, v101
	v_and_b32_e32 v35, 3, v1
	v_lshlrev_b32_e32 v36, 2, v79
	s_mul_i32 s2, s92, 48
	s_mul_i32 s10, s10, 48
	s_mul_i32 s3, s82, 48
	v_cmp_gt_u32_e64 s[0:1], s0, v162
	v_add_u32_e32 v34, 0xa000, v33
	v_cmp_ne_u32_e64 s[4:5], 2, v35
	v_add_u32_e32 v37, 0, v36
	v_mul_u32_u24_e32 v38, 0x3000, v79
	s_sub_i32 s2, s2, s10
	s_sub_i32 s21, s3, s10
	s_mov_b64 s[8:9], 0x7e0000
	s_movk_i32 s22, 0x757
	v_add_u32_e32 v39, v0, v100
	v_readlane_b32 s53, v241, 2
	v_readlane_b32 s54, v241, 3
	v_readlane_b32 s55, v241, 4
	v_readlane_b32 s56, v241, 5
	v_readlane_b32 s57, v241, 6
	v_readlane_b32 s58, v241, 7
	v_readlane_b32 s59, v241, 8
	v_readlane_b32 s62, v241, 11
	v_readlane_b32 s63, v241, 12
	v_readlane_b32 s64, v241, 13
	v_readlane_b32 s65, v241, 14
	v_readlane_b32 s66, v241, 15
	v_readlane_b32 s67, v241, 16
	s_branch .LBB0_591
